# attention: full per-row shift test + rescale block out of line; quick test falls through into exp/PV
# speedup vs baseline: 1.0066x; 1.0016x over previous
.LBB0_885:
	s_nop 8
	s_cmp_lg_u64 s[64:65], 0
	s_cbranch_scc1 .Lhwat0_full
	v_max_f32_e32 v203, v80, v81
	v_max_f32_e32 v205, v64, v65
	v_max3_f32 v203, v203, v82, v83
	v_max3_f32 v205, v205, v66, v67
	v_max3_f32 v203, v203, v84, v85
	v_max3_f32 v205, v205, v68, v69
	v_max3_f32 v203, v203, v86, v87
	v_max3_f32 v205, v205, v70, v71
	v_max3_f32 v203, v203, v88, v89
	v_max3_f32 v205, v205, v72, v73
	v_max3_f32 v203, v203, v90, v91
	v_max3_f32 v205, v205, v74, v75
	v_max3_f32 v203, v203, v92, v93
	v_max3_f32 v205, v205, v76, v77
	v_max3_f32 v203, v203, v94, v95
	v_max3_f32 v205, v205, v78, v79
	v_max_f32_e32 v204, v203, v205
	v_cmp_lt_f32_e32 vcc, s83, v204
	s_cbranch_vccnz .Lhwat0_full

.LBB0_883:
	s_andn2_b64 vcc, exec, s[28:29]
	s_cbranch_vccnz .LBB0_885
	v_mad_u32_u24 v203, v203, s82, v201
	ds_read_b128 v[204:207], v203
	ds_read_b128 v[208:211], v203 offset:32
	s_nop 5
	v_xor_b32_e32 v80, 0x80000000, v199
	v_xor_b32_e32 v64, 0x80000000, v200
	v_mov_b32_e32 v81, v80
	v_mov_b32_e32 v82, v80
	v_mov_b32_e32 v83, v80
	v_mov_b32_e32 v84, v80
	v_mov_b32_e32 v85, v80
	v_mov_b32_e32 v86, v80
	v_mov_b32_e32 v87, v80
	v_mov_b32_e32 v88, v80
	v_mov_b32_e32 v89, v80
	v_mov_b32_e32 v90, v80
	v_mov_b32_e32 v91, v80
	v_mov_b32_e32 v92, v80
	v_mov_b32_e32 v93, v80
	v_mov_b32_e32 v94, v80
	v_mov_b32_e32 v95, v80
	v_mov_b32_e32 v65, v64
	v_mov_b32_e32 v66, v64
	v_mov_b32_e32 v67, v64
	v_mov_b32_e32 v68, v64
	v_mov_b32_e32 v69, v64
	v_mov_b32_e32 v70, v64
	v_mov_b32_e32 v71, v64
	v_mov_b32_e32 v72, v64
	v_mov_b32_e32 v73, v64
	v_mov_b32_e32 v74, v64
	v_mov_b32_e32 v75, v64
	v_mov_b32_e32 v76, v64
	v_mov_b32_e32 v77, v64
	v_mov_b32_e32 v78, v64
	v_mov_b32_e32 v79, v64
	s_waitcnt lgkmcnt(0)
	v_mfma_f32_32x32x16_bf16 v[80:95], v[204:207], v[96:99], v[80:95]
	v_mfma_f32_32x32x16_bf16 v[64:79], v[204:207], v[136:139], v[64:79]
	v_mfma_f32_32x32x16_bf16 v[80:95], v[208:211], v[100:103], v[80:95]
	v_mfma_f32_32x32x16_bf16 v[64:79], v[208:211], v[120:123], v[64:79]
	ds_read_b128 v[204:207], v203 offset:64
	ds_read_b128 v[208:211], v203 offset:96
	s_waitcnt lgkmcnt(0)
	v_mfma_f32_32x32x16_bf16 v[80:95], v[204:207], v[104:107], v[80:95]
	v_mfma_f32_32x32x16_bf16 v[64:79], v[204:207], v[124:127], v[64:79]
	v_mfma_f32_32x32x16_bf16 v[80:95], v[208:211], v[108:111], v[80:95]
	v_mfma_f32_32x32x16_bf16 v[64:79], v[208:211], v[128:131], v[64:79]
	ds_read_b128 v[204:207], v203 offset:128
	ds_read_b128 v[208:211], v203 offset:160
	s_waitcnt lgkmcnt(0)
	v_mfma_f32_32x32x16_bf16 v[80:95], v[204:207], v[112:115], v[80:95]
	v_mfma_f32_32x32x16_bf16 v[64:79], v[204:207], v[132:135], v[64:79]
	v_mfma_f32_32x32x16_bf16 v[80:95], v[208:211], v[116:119], v[80:95]
	v_mfma_f32_32x32x16_bf16 v[64:79], v[208:211], v[140:143], v[64:79]
	s_branch .LBB0_885
.Lhwat0_full:
	v_max_f32_e32 v203, v80, v81
	v_max_f32_e32 v205, v64, v65
	v_max3_f32 v203, v203, v82, v83
	v_max3_f32 v205, v205, v66, v67
	v_max3_f32 v203, v203, v84, v85
	v_max3_f32 v205, v205, v68, v69
	v_max3_f32 v203, v203, v86, v87
	v_max3_f32 v205, v205, v70, v71
	v_max3_f32 v203, v203, v88, v89
	v_max3_f32 v205, v205, v72, v73
	v_max3_f32 v203, v203, v90, v91
	v_max3_f32 v205, v205, v74, v75
	v_max3_f32 v203, v203, v92, v93
	v_max3_f32 v205, v205, v76, v77
	v_max3_f32 v203, v203, v94, v95
	v_max3_f32 v205, v205, v78, v79
	s_nop 1
	v_permlane32_swap_b32_e32 v203, v205
	v_max_f32_e32 v204, v203, v205
	v_cmp_lt_f32_e32 vcc, s83, v204
	s_cmp_lg_u64 s[64:65], 0
	s_cbranch_scc1 .Lhwat0_firstchk
	s_cbranch_vccz .LBB0_887
	s_branch .Lhwat0_rare

.Lhwat0_rare:
	v_mov_b32_e32 v203, v204
	s_nop 1
	v_permlane32_swap_b32_e32 v204, v203
	v_max_f32_e32 v205, v204, v204
	v_max_f32_e32 v205, 0, v205
	v_cndmask_b32_e64 v204, v205, v204, s[64:65]
	v_exp_f32_e64 v206, -v204
	v_add_f32_e32 v199, v199, v204
	v_pk_add_f32 v[80:81], v[80:81], v[204:205] op_sel_hi:[1,0] neg_lo:[0,1] neg_hi:[0,1]
	v_pk_add_f32 v[82:83], v[82:83], v[204:205] op_sel_hi:[1,0] neg_lo:[0,1] neg_hi:[0,1]
	v_pk_add_f32 v[84:85], v[84:85], v[204:205] op_sel_hi:[1,0] neg_lo:[0,1] neg_hi:[0,1]
	v_pk_add_f32 v[86:87], v[86:87], v[204:205] op_sel_hi:[1,0] neg_lo:[0,1] neg_hi:[0,1]
	v_pk_add_f32 v[88:89], v[88:89], v[204:205] op_sel_hi:[1,0] neg_lo:[0,1] neg_hi:[0,1]
	v_pk_add_f32 v[90:91], v[90:91], v[204:205] op_sel_hi:[1,0] neg_lo:[0,1] neg_hi:[0,1]
	v_pk_add_f32 v[92:93], v[92:93], v[204:205] op_sel_hi:[1,0] neg_lo:[0,1] neg_hi:[0,1]
	v_pk_add_f32 v[94:95], v[94:95], v[204:205] op_sel_hi:[1,0] neg_lo:[0,1] neg_hi:[0,1]
	v_max_f32_e32 v204, v203, v203
	v_max_f32_e32 v204, 0, v204
	v_cndmask_b32_e64 v204, v204, v203, s[64:65]
	v_exp_f32_e64 v208, -v204
	v_mov_b32_e32 v209, v206
	v_pk_mul_f32 v[62:63], v[62:63], v[206:207] op_sel_hi:[1,0]
	v_pk_mul_f32 v[60:61], v[60:61], v[206:207] op_sel_hi:[1,0]
	v_pk_mul_f32 v[58:59], v[58:59], v[206:207] op_sel_hi:[1,0]
	v_pk_mul_f32 v[56:57], v[56:57], v[206:207] op_sel_hi:[1,0]
	v_pk_mul_f32 v[54:55], v[54:55], v[206:207] op_sel_hi:[1,0]
	v_pk_mul_f32 v[52:53], v[52:53], v[206:207] op_sel_hi:[1,0]
	v_pk_mul_f32 v[50:51], v[50:51], v[206:207] op_sel_hi:[1,0]
	v_pk_mul_f32 v[48:49], v[48:49], v[206:207] op_sel_hi:[1,0]
	v_pk_mul_f32 v[46:47], v[46:47], v[206:207] op_sel_hi:[1,0]
	v_pk_mul_f32 v[44:45], v[44:45], v[206:207] op_sel_hi:[1,0]
	v_pk_mul_f32 v[42:43], v[42:43], v[206:207] op_sel_hi:[1,0]
	v_pk_mul_f32 v[40:41], v[40:41], v[206:207] op_sel_hi:[1,0]
	v_pk_mul_f32 v[38:39], v[38:39], v[206:207] op_sel_hi:[1,0]
	v_pk_mul_f32 v[36:37], v[36:37], v[206:207] op_sel_hi:[1,0]
	v_pk_mul_f32 v[34:35], v[34:35], v[206:207] op_sel_hi:[1,0]
	v_pk_mul_f32 v[32:33], v[32:33], v[206:207] op_sel_hi:[1,0]
	v_add_f32_e32 v200, v200, v204
	v_pk_mul_f32 v[150:151], v[150:151], v[208:209]
	v_pk_add_f32 v[64:65], v[64:65], v[204:205] op_sel_hi:[1,0] neg_lo:[0,1] neg_hi:[0,1]
	v_pk_add_f32 v[66:67], v[66:67], v[204:205] op_sel_hi:[1,0] neg_lo:[0,1] neg_hi:[0,1]
	v_pk_add_f32 v[68:69], v[68:69], v[204:205] op_sel_hi:[1,0] neg_lo:[0,1] neg_hi:[0,1]
	v_pk_add_f32 v[70:71], v[70:71], v[204:205] op_sel_hi:[1,0] neg_lo:[0,1] neg_hi:[0,1]
	v_pk_add_f32 v[72:73], v[72:73], v[204:205] op_sel_hi:[1,0] neg_lo:[0,1] neg_hi:[0,1]
	v_pk_add_f32 v[74:75], v[74:75], v[204:205] op_sel_hi:[1,0] neg_lo:[0,1] neg_hi:[0,1]
	v_pk_add_f32 v[76:77], v[76:77], v[204:205] op_sel_hi:[1,0] neg_lo:[0,1] neg_hi:[0,1]
	v_pk_add_f32 v[78:79], v[78:79], v[204:205] op_sel_hi:[1,0] neg_lo:[0,1] neg_hi:[0,1]
	v_pk_mul_f32 v[30:31], v[30:31], v[208:209] op_sel_hi:[1,0]
	v_pk_mul_f32 v[28:29], v[28:29], v[208:209] op_sel_hi:[1,0]
	v_pk_mul_f32 v[26:27], v[26:27], v[208:209] op_sel_hi:[1,0]
	v_pk_mul_f32 v[24:25], v[24:25], v[208:209] op_sel_hi:[1,0]
	v_pk_mul_f32 v[22:23], v[22:23], v[208:209] op_sel_hi:[1,0]
	v_pk_mul_f32 v[20:21], v[20:21], v[208:209] op_sel_hi:[1,0]
	v_pk_mul_f32 v[18:19], v[18:19], v[208:209] op_sel_hi:[1,0]
	v_pk_mul_f32 v[16:17], v[16:17], v[208:209] op_sel_hi:[1,0]
	v_pk_mul_f32 v[14:15], v[14:15], v[208:209] op_sel_hi:[1,0]
	v_pk_mul_f32 v[12:13], v[12:13], v[208:209] op_sel_hi:[1,0]
	v_pk_mul_f32 v[10:11], v[10:11], v[208:209] op_sel_hi:[1,0]
	v_pk_mul_f32 v[8:9], v[8:9], v[208:209] op_sel_hi:[1,0]
	v_pk_mul_f32 v[6:7], v[6:7], v[208:209] op_sel_hi:[1,0]
	v_pk_mul_f32 v[4:5], v[4:5], v[208:209] op_sel_hi:[1,0]
	v_pk_mul_f32 v[2:3], v[2:3], v[208:209] op_sel_hi:[1,0]
	v_pk_mul_f32 v[0:1], v[0:1], v[208:209] op_sel_hi:[1,0]
	s_mov_b64 s[62:63], -1
	s_branch .LBB0_887

.LBB0_2119:
	s_nop 8
	s_cmp_lg_u64 s[64:65], 0
	s_cbranch_scc1 .Lhwat1_full
	v_max_f32_e32 v203, v80, v81
	v_max_f32_e32 v205, v64, v65
	v_max3_f32 v203, v203, v82, v83
	v_max3_f32 v205, v205, v66, v67
	v_max3_f32 v203, v203, v84, v85
	v_max3_f32 v205, v205, v68, v69
	v_max3_f32 v203, v203, v86, v87
	v_max3_f32 v205, v205, v70, v71
	v_max3_f32 v203, v203, v88, v89
	v_max3_f32 v205, v205, v72, v73
	v_max3_f32 v203, v203, v90, v91
	v_max3_f32 v205, v205, v74, v75
	v_max3_f32 v203, v203, v92, v93
	v_max3_f32 v205, v205, v76, v77
	v_max3_f32 v203, v203, v94, v95
	v_max3_f32 v205, v205, v78, v79
	v_max_f32_e32 v204, v203, v205
	v_cmp_lt_f32_e32 vcc, s82, v204
	s_cbranch_vccnz .Lhwat1_full

.LBB0_2117:
	s_andn2_b64 vcc, exec, s[34:35]
	s_cbranch_vccnz .LBB0_2119
	v_mad_u32_u24 v203, v203, s81, v201
	ds_read_b128 v[204:207], v203
	ds_read_b128 v[208:211], v203 offset:32
	s_nop 5
	v_xor_b32_e32 v80, 0x80000000, v199
	v_xor_b32_e32 v64, 0x80000000, v200
	v_mov_b32_e32 v81, v80
	v_mov_b32_e32 v82, v80
	v_mov_b32_e32 v83, v80
	v_mov_b32_e32 v84, v80
	v_mov_b32_e32 v85, v80
	v_mov_b32_e32 v86, v80
	v_mov_b32_e32 v87, v80
	v_mov_b32_e32 v88, v80
	v_mov_b32_e32 v89, v80
	v_mov_b32_e32 v90, v80
	v_mov_b32_e32 v91, v80
	v_mov_b32_e32 v92, v80
	v_mov_b32_e32 v93, v80
	v_mov_b32_e32 v94, v80
	v_mov_b32_e32 v95, v80
	v_mov_b32_e32 v65, v64
	v_mov_b32_e32 v66, v64
	v_mov_b32_e32 v67, v64
	v_mov_b32_e32 v68, v64
	v_mov_b32_e32 v69, v64
	v_mov_b32_e32 v70, v64
	v_mov_b32_e32 v71, v64
	v_mov_b32_e32 v72, v64
	v_mov_b32_e32 v73, v64
	v_mov_b32_e32 v74, v64
	v_mov_b32_e32 v75, v64
	v_mov_b32_e32 v76, v64
	v_mov_b32_e32 v77, v64
	v_mov_b32_e32 v78, v64
	v_mov_b32_e32 v79, v64
	s_waitcnt lgkmcnt(0)
	v_mfma_f32_32x32x16_bf16 v[80:95], v[204:207], v[96:99], v[80:95]
	v_mfma_f32_32x32x16_bf16 v[64:79], v[204:207], v[136:139], v[64:79]
	v_mfma_f32_32x32x16_bf16 v[80:95], v[208:211], v[100:103], v[80:95]
	v_mfma_f32_32x32x16_bf16 v[64:79], v[208:211], v[120:123], v[64:79]
	ds_read_b128 v[204:207], v203 offset:64
	ds_read_b128 v[208:211], v203 offset:96
	s_waitcnt lgkmcnt(0)
	v_mfma_f32_32x32x16_bf16 v[80:95], v[204:207], v[104:107], v[80:95]
	v_mfma_f32_32x32x16_bf16 v[64:79], v[204:207], v[124:127], v[64:79]
	v_mfma_f32_32x32x16_bf16 v[80:95], v[208:211], v[108:111], v[80:95]
	v_mfma_f32_32x32x16_bf16 v[64:79], v[208:211], v[128:131], v[64:79]
	ds_read_b128 v[204:207], v203 offset:128
	ds_read_b128 v[208:211], v203 offset:160
	s_waitcnt lgkmcnt(0)
	v_mfma_f32_32x32x16_bf16 v[80:95], v[204:207], v[112:115], v[80:95]
	v_mfma_f32_32x32x16_bf16 v[64:79], v[204:207], v[132:135], v[64:79]
	v_mfma_f32_32x32x16_bf16 v[80:95], v[208:211], v[116:119], v[80:95]
	v_mfma_f32_32x32x16_bf16 v[64:79], v[208:211], v[140:143], v[64:79]
	s_branch .LBB0_2119
.Lhwat1_full:
	v_max_f32_e32 v203, v80, v81
	v_max_f32_e32 v205, v64, v65
	v_max3_f32 v203, v203, v82, v83
	v_max3_f32 v205, v205, v66, v67
	v_max3_f32 v203, v203, v84, v85
	v_max3_f32 v205, v205, v68, v69
	v_max3_f32 v203, v203, v86, v87
	v_max3_f32 v205, v205, v70, v71
	v_max3_f32 v203, v203, v88, v89
	v_max3_f32 v205, v205, v72, v73
	v_max3_f32 v203, v203, v90, v91
	v_max3_f32 v205, v205, v74, v75
	v_max3_f32 v203, v203, v92, v93
	v_max3_f32 v205, v205, v76, v77
	v_max3_f32 v203, v203, v94, v95
	v_max3_f32 v205, v205, v78, v79
	s_nop 1
	v_permlane32_swap_b32_e32 v203, v205
	v_max_f32_e32 v204, v203, v205
	v_cmp_lt_f32_e32 vcc, s82, v204
	s_cmp_lg_u64 s[64:65], 0
	s_cbranch_scc1 .Lhwat1_firstchk
	s_cbranch_vccz .LBB0_2121
	s_branch .Lhwat1_rare
